# s_not mask inversions with the embedded LDS staging writes before MFMA 18 (three MFMAs of cover)
# speedup vs baseline: 1.0035x; 1.0035x over previous
.Lp1a_end:
	s_waitcnt lgkmcnt(11)
	v_mfma_f32_32x32x16_bf16 v[82:97], v[164:167], v[126:129], v[82:97]
	v_exp_f32_e32 v62, v62
	v_add_f32_e32 v200, v200, v54
	v_exp_f32_e32 v63, v63
	v_add_f32_e32 v201, v201, v55
	v_exp_f32_e32 v64, v64
	s_waitcnt lgkmcnt(10)
	v_mfma_f32_32x32x16_bf16 v[98:113], v[168:171], v[126:129], v[98:113]
	ds_read2_b64 v[164:167], v242 offset0:4 offset1:6
	ds_read2_b64 v[168:171], v163 offset0:36 offset1:38
	v_add_f32_e32 v200, v200, v56
	v_exp_f32_e32 v65, v65
	v_add_f32_e32 v201, v201, v57
	v_cvt_pk_bf16_f32 v228, v58, v59
	v_cvt_pk_bf16_f32 v229, v60, v61
	s_waitcnt lgkmcnt(11)
	v_mfma_f32_32x32x16_bf16 v[18:33], v[238:241], v[224:227], v[18:33]
	v_cvt_pk_bf16_f32 v230, v62, v63
	v_cvt_pk_bf16_f32 v231, v64, v65
	v_exp_f32_e32 v66, v66
	v_add_f32_e32 v200, v200, v58
	v_exp_f32_e32 v67, v67
	v_add_f32_e32 v201, v201, v59
	s_waitcnt lgkmcnt(10)
	v_mfma_f32_32x32x16_bf16 v[34:49], v[234:237], v[224:227], v[34:49]
	v_exp_f32_e32 v68, v68
	v_add_f32_e32 v200, v200, v60
	v_exp_f32_e32 v69, v69
	v_add_f32_e32 v201, v201, v61
	v_exp_f32_e32 v70, v70
	s_waitcnt lgkmcnt(9)
	v_mfma_f32_32x32x16_bf16 v[82:97], v[172:175], v[134:137], v[82:97]
	v_add_f32_e32 v200, v200, v62
	v_exp_f32_e32 v71, v71
	v_add_f32_e32 v201, v201, v63
	v_exp_f32_e32 v72, v72
	v_add_f32_e32 v200, v200, v64
	s_waitcnt lgkmcnt(8)
	v_mfma_f32_32x32x16_bf16 v[98:113], v[176:179], v[134:137], v[98:113]
	ds_read2_b64 v[172:175], v242 offset0:8 offset1:10
	ds_read2_b64 v[176:179], v163 offset0:40 offset1:42
	v_exp_f32_e32 v73, v73
	v_add_f32_e32 v201, v201, v65
	v_cvt_pk_bf16_f32 v224, v66, v67
	v_cvt_pk_bf16_f32 v225, v68, v69
	v_cvt_pk_bf16_f32 v226, v70, v71
	s_waitcnt lgkmcnt(3)
	v_mfma_f32_32x32x16_bf16 v[18:33], v[164:167], v[228:231], v[18:33]
	v_cvt_pk_bf16_f32 v227, v72, v73
	v_exp_f32_e32 v74, v74
	v_add_f32_e32 v200, v200, v66
	v_exp_f32_e32 v75, v75
	v_add_f32_e32 v201, v201, v67
	s_waitcnt lgkmcnt(2)
	v_mfma_f32_32x32x16_bf16 v[34:49], v[168:171], v[228:231], v[34:49]
	v_exp_f32_e32 v76, v76
	v_add_f32_e32 v200, v200, v68
	v_exp_f32_e32 v77, v77
	v_add_f32_e32 v201, v201, v69
	v_exp_f32_e32 v78, v78
	s_waitcnt lgkmcnt(9)
	v_mfma_f32_32x32x16_bf16 v[82:97], v[180:183], v[138:141], v[82:97]
	v_add_f32_e32 v200, v200, v70
	v_exp_f32_e32 v79, v79
	v_add_f32_e32 v201, v201, v71
	v_exp_f32_e32 v80, v80
	v_add_f32_e32 v200, v200, v72
	s_waitcnt lgkmcnt(8)
	v_mfma_f32_32x32x16_bf16 v[98:113], v[184:187], v[138:141], v[98:113]
	ds_read2_b64 v[180:183], v242 offset0:12 offset1:14
	ds_read2_b64 v[184:187], v163 offset0:44 offset1:46
	v_exp_f32_e32 v81, v81
	v_add_f32_e32 v201, v201, v73
	v_cvt_pk_bf16_f32 v228, v74, v75
	v_cvt_pk_bf16_f32 v229, v76, v77
	v_cvt_pk_bf16_f32 v230, v78, v79
	s_waitcnt lgkmcnt(3)
	v_mfma_f32_32x32x16_bf16 v[18:33], v[172:175], v[224:227], v[18:33]
	v_cvt_pk_bf16_f32 v231, v80, v81
	v_add_f32_e32 v200, v200, v74
	v_add_f32_e32 v201, v201, v75
	v_add_f32_e32 v200, v200, v76
	v_add_f32_e32 v201, v201, v77
	v_add_f32_e32 v200, v200, v78
	v_add_f32_e32 v201, v201, v79
	v_add_f32_e32 v200, v200, v80
	s_waitcnt lgkmcnt(2)
	v_mfma_f32_32x32x16_bf16 v[34:49], v[176:179], v[224:227], v[34:49]
	v_add_f32_e32 v201, v201, v81
	v_add_f32_e32 v200, v200, v201
	v_add_f32_e32 v162, v162, v200
	s_waitcnt lgkmcnt(9)
	v_mfma_f32_32x32x16_bf16 v[82:97], v[188:191], v[142:145], v[82:97]
	s_waitcnt lgkmcnt(8)
	v_mfma_f32_32x32x16_bf16 v[98:113], v[192:195], v[142:145], v[98:113]
	s_waitcnt lgkmcnt(7)
	v_mfma_f32_32x32x16_bf16 v[82:97], v[196:199], v[146:149], v[82:97]
	s_waitcnt lgkmcnt(0)
	s_not_b64 s[42:43], s[44:45]
	s_andn2_b64 vcc, exec, s[44:45]
	s_cbranch_vccnz .Lt1a_mid
	s_and_b32 s44, s53, 2
	s_mulk_i32 s44, 0x3400
	s_add_i32 s62, s44, 0
	v_add_u32_e32 v0, s62, v151
	s_waitcnt vmcnt(0)
	ds_write_b128 v0, v[118:121]
	s_and_saveexec_b64 s[44:45], s[40:41]
	v_add_u32_e32 v0, s62, v159
	ds_write_b128 v0, v[6:9]
	s_or_b64 exec, exec, s[44:45]

.Lp2a_end:
	s_waitcnt lgkmcnt(11)
	v_mfma_f32_32x32x16_bf16 v[50:65], v[164:167], v[126:129], v[50:65]
	v_exp_f32_e32 v94, v94
	v_add_f32_e32 v200, v200, v86
	v_exp_f32_e32 v95, v95
	v_add_f32_e32 v201, v201, v87
	v_exp_f32_e32 v96, v96
	s_waitcnt lgkmcnt(10)
	v_mfma_f32_32x32x16_bf16 v[66:81], v[168:171], v[126:129], v[66:81]
	ds_read2_b64 v[164:167], v242 offset0:4 offset1:6
	ds_read2_b64 v[168:171], v163 offset0:36 offset1:38
	v_add_f32_e32 v200, v200, v88
	v_exp_f32_e32 v97, v97
	v_add_f32_e32 v201, v201, v89
	v_cvt_pk_bf16_f32 v228, v90, v91
	v_cvt_pk_bf16_f32 v229, v92, v93
	s_waitcnt lgkmcnt(11)
	v_mfma_f32_32x32x16_bf16 v[18:33], v[238:241], v[224:227], v[18:33]
	v_cvt_pk_bf16_f32 v230, v94, v95
	v_cvt_pk_bf16_f32 v231, v96, v97
	v_exp_f32_e32 v98, v98
	v_add_f32_e32 v200, v200, v90
	v_exp_f32_e32 v99, v99
	v_add_f32_e32 v201, v201, v91
	s_waitcnt lgkmcnt(10)
	v_mfma_f32_32x32x16_bf16 v[34:49], v[234:237], v[224:227], v[34:49]
	v_exp_f32_e32 v100, v100
	v_add_f32_e32 v200, v200, v92
	v_exp_f32_e32 v101, v101
	v_add_f32_e32 v201, v201, v93
	v_exp_f32_e32 v102, v102
	s_waitcnt lgkmcnt(9)
	v_mfma_f32_32x32x16_bf16 v[50:65], v[172:175], v[134:137], v[50:65]
	v_add_f32_e32 v200, v200, v94
	v_exp_f32_e32 v103, v103
	v_add_f32_e32 v201, v201, v95
	v_exp_f32_e32 v104, v104
	v_add_f32_e32 v200, v200, v96
	s_waitcnt lgkmcnt(8)
	v_mfma_f32_32x32x16_bf16 v[66:81], v[176:179], v[134:137], v[66:81]
	ds_read2_b64 v[172:175], v242 offset0:8 offset1:10
	ds_read2_b64 v[176:179], v163 offset0:40 offset1:42
	v_exp_f32_e32 v105, v105
	v_add_f32_e32 v201, v201, v97
	v_cvt_pk_bf16_f32 v224, v98, v99
	v_cvt_pk_bf16_f32 v225, v100, v101
	v_cvt_pk_bf16_f32 v226, v102, v103
	s_waitcnt lgkmcnt(3)
	v_mfma_f32_32x32x16_bf16 v[18:33], v[164:167], v[228:231], v[18:33]
	v_cvt_pk_bf16_f32 v227, v104, v105
	v_exp_f32_e32 v106, v106
	v_add_f32_e32 v200, v200, v98
	v_exp_f32_e32 v107, v107
	v_add_f32_e32 v201, v201, v99
	s_waitcnt lgkmcnt(2)
	v_mfma_f32_32x32x16_bf16 v[34:49], v[168:171], v[228:231], v[34:49]
	v_exp_f32_e32 v108, v108
	v_add_f32_e32 v200, v200, v100
	v_exp_f32_e32 v109, v109
	v_add_f32_e32 v201, v201, v101
	v_exp_f32_e32 v110, v110
	s_waitcnt lgkmcnt(9)
	v_mfma_f32_32x32x16_bf16 v[50:65], v[180:183], v[138:141], v[50:65]
	v_add_f32_e32 v200, v200, v102
	v_exp_f32_e32 v111, v111
	v_add_f32_e32 v201, v201, v103
	v_exp_f32_e32 v112, v112
	v_add_f32_e32 v200, v200, v104
	s_waitcnt lgkmcnt(8)
	v_mfma_f32_32x32x16_bf16 v[66:81], v[184:187], v[138:141], v[66:81]
	ds_read2_b64 v[180:183], v242 offset0:12 offset1:14
	ds_read2_b64 v[184:187], v163 offset0:44 offset1:46
	v_exp_f32_e32 v113, v113
	v_add_f32_e32 v201, v201, v105
	v_cvt_pk_bf16_f32 v228, v106, v107
	v_cvt_pk_bf16_f32 v229, v108, v109
	v_cvt_pk_bf16_f32 v230, v110, v111
	s_waitcnt lgkmcnt(3)
	v_mfma_f32_32x32x16_bf16 v[18:33], v[172:175], v[224:227], v[18:33]
	v_cvt_pk_bf16_f32 v231, v112, v113
	v_add_f32_e32 v200, v200, v106
	v_add_f32_e32 v201, v201, v107
	v_add_f32_e32 v200, v200, v108
	v_add_f32_e32 v201, v201, v109
	v_add_f32_e32 v200, v200, v110
	v_add_f32_e32 v201, v201, v111
	v_add_f32_e32 v200, v200, v112
	s_waitcnt lgkmcnt(2)
	v_mfma_f32_32x32x16_bf16 v[34:49], v[176:179], v[224:227], v[34:49]
	v_add_f32_e32 v201, v201, v113
	v_add_f32_e32 v200, v200, v201
	v_add_f32_e32 v162, v162, v200
	s_waitcnt lgkmcnt(9)
	v_mfma_f32_32x32x16_bf16 v[50:65], v[188:191], v[142:145], v[50:65]
	s_waitcnt lgkmcnt(8)
	v_mfma_f32_32x32x16_bf16 v[66:81], v[192:195], v[142:145], v[66:81]
	s_waitcnt lgkmcnt(7)
	v_mfma_f32_32x32x16_bf16 v[50:65], v[196:199], v[146:149], v[50:65]
	s_waitcnt lgkmcnt(0)
	s_mul_i32 s58, s25, 0x2200
	s_and_b64 vcc, exec, s[44:45]
	s_cbranch_vccnz .Lt2a_mid
	s_and_b32 s44, s60, 3
	s_mulk_i32 s44, 0x3400
	s_add_i32 s52, s44, 0
	v_add_u32_e32 v0, s52, v151
	s_waitcnt vmcnt(0)
	ds_write_b128 v0, v[2:5]
	s_and_saveexec_b64 s[44:45], s[40:41]
	v_add_u32_e32 v0, s52, v159
	ds_write_b128 v0, v[10:13]
	s_or_b64 exec, exec, s[44:45]
